# deferred w_down conversion with 16 tiles per idle wave (5376 tiles out of phase 0)
# speedup vs baseline: 1.0026x; 1.0018x over previous
.Ldf_go:
	s_add_i32 s88, s88, s87
	s_add_i32 s85, s88, 0x9c00
	v_readlane_b32 s90, v254, 10
	v_readlane_b32 s91, v254, 11
	s_mov_b64 s[80:81], 0x80
	s_mov_b64 s[82:83], 0xc0
	v_and_b32_e32 v1, 63, v226
	v_lshlrev_b32_e32 v66, 4, v1
	v_lshlrev_b32_e32 v3, 6, v1
	v_and_b32_e32 v70, 0x180, v3
	v_lshlrev_b32_e32 v2, 2, v1
	v_and_b32_e32 v71, 28, v2
	v_and_b32_e32 v2, 24, v226
	v_mov_b32_e32 v69, 0
	v_lshlrev_b32_e32 v68, 1, v70
	v_lshl_add_u64 v[76:77], s[26:27], 0, v[68:69]
	v_lshlrev_b32_e32 v4, 1, v2
	v_mov_b32_e32 v5, v69
	v_lshl_add_u64 v[78:79], v[76:77], 0, v[4:5]
	v_and_b32_e32 v67, 56, v226
	v_and_b32_e32 v84, 16, v66
	v_lshlrev_b32_e32 v68, 1, v2
